# attention: next key tile K fragments read from LDS inside the PV MFMA block (registers already consumed), QK starts without exposed LDS latency
# speedup vs baseline: 1.0008x; 1.0008x over previous
.LBB0_815:
	s_mov_b32 s24, 0
	s_mov_b32 s25, 0
	s_mul_i32 s14, s10, 0x8a00
	s_cmp_eq_u32 s9, 0
	s_mov_b32 s13, 0
	s_cselect_b64 s[36:37], -1, 0
	v_add_u32_e32 v188, s14, v186
	v_add_u32_e32 v189, s14, v187

.Latt_noskip:
	s_setprio 1
	s_cmp_eq_u32 s25, 0
	s_cbranch_scc0 .Latt_qkp
	ds_read_b128 v[64:67], v189
	ds_read_b128 v[164:167], v189 offset:32
	ds_read_b128 v[168:171], v189 offset:64
	ds_read_b128 v[172:175], v189 offset:96
	s_waitcnt lgkmcnt(3)
	v_mfma_f32_32x32x16_bf16 v[80:95], v[64:67], v[96:99], v[206:221]
	v_mfma_f32_32x32x16_bf16 v[64:79], v[64:67], v[112:115], v[222:237]
	s_waitcnt lgkmcnt(2)
	v_mfma_f32_32x32x16_bf16 v[80:95], v[164:167], v[100:103], v[80:95]
	v_mfma_f32_32x32x16_bf16 v[64:79], v[164:167], v[116:119], v[64:79]
	s_branch .Latt_qk2
.Latt_qkp:
	s_waitcnt lgkmcnt(2)
	v_mfma_f32_32x32x16_bf16 v[80:95], v[64:67], v[96:99], v[206:221]
	v_mfma_f32_32x32x16_bf16 v[64:79], v[64:67], v[112:115], v[222:237]
	v_mfma_f32_32x32x16_bf16 v[80:95], v[164:167], v[100:103], v[80:95]
	v_mfma_f32_32x32x16_bf16 v[64:79], v[164:167], v[116:119], v[64:79]
.Latt_qk2:
	s_waitcnt lgkmcnt(1)
	v_mfma_f32_32x32x16_bf16 v[80:95], v[168:171], v[104:107], v[80:95]
	v_mfma_f32_32x32x16_bf16 v[64:79], v[168:171], v[120:123], v[64:79]
	s_waitcnt lgkmcnt(0)
	v_mfma_f32_32x32x16_bf16 v[80:95], v[172:175], v[108:111], v[80:95]
	v_mfma_f32_32x32x16_bf16 v[64:79], v[172:175], v[124:127], v[64:79]
	s_setprio 0
	s_cmp_lt_i32 s9, 2
	s_cbranch_scc1 .LBB0_818
	s_cmp_eq_u32 s9, 2
	s_cselect_b64 s[50:51], -1, 0
	s_cbranch_execz .LBB0_819
	s_branch .LBB0_820

.LBB0_822:
	s_nop 2
	s_cmp_lg_u32 s24, 0
	s_cbranch_scc1 .Latt_slow
	ds_read2_b64 v[164:167], v188 offset1:2
	v_add_u32_e32 v201, 0x2000, v188
	ds_read2_b64 v[168:171], v201 offset0:32 offset1:34
	ds_read2_b64 v[172:175], v188 offset0:4 offset1:6
	ds_read2_b64 v[238:241], v201 offset0:36 offset1:38
	v_exp_f32_e32 v80, v80
	v_exp_f32_e32 v64, v64
	v_exp_f32_e32 v81, v81
	v_exp_f32_e32 v65, v65
	v_exp_f32_e32 v82, v82
	v_exp_f32_e32 v66, v66
	v_exp_f32_e32 v83, v83
	v_exp_f32_e32 v67, v67
	v_exp_f32_e32 v84, v84
	v_exp_f32_e32 v68, v68
	v_exp_f32_e32 v85, v85
	v_exp_f32_e32 v69, v69
	v_exp_f32_e32 v86, v86
	v_exp_f32_e32 v70, v70
	v_exp_f32_e32 v87, v87
	v_exp_f32_e32 v71, v71
	v_exp_f32_e32 v88, v88
	v_exp_f32_e32 v72, v72
	v_exp_f32_e32 v89, v89
	v_exp_f32_e32 v73, v73
	v_exp_f32_e32 v90, v90
	v_exp_f32_e32 v74, v74
	v_exp_f32_e32 v91, v91
	v_exp_f32_e32 v75, v75
	v_exp_f32_e32 v92, v92
	v_exp_f32_e32 v76, v76
	v_exp_f32_e32 v93, v93
	v_exp_f32_e32 v77, v77
	v_exp_f32_e32 v94, v94
	v_exp_f32_e32 v78, v78
	v_exp_f32_e32 v95, v95
	v_exp_f32_e32 v79, v79
	v_add_f32_e32 v197, v80, v81
	v_add_f32_e32 v198, v64, v65
	v_add_f32_e32 v197, v197, v82
	v_add_f32_e32 v198, v198, v66
	v_add_f32_e32 v197, v197, v83
	v_add_f32_e32 v198, v198, v67
	v_add_f32_e32 v197, v197, v84
	v_add_f32_e32 v198, v198, v68
	v_add_f32_e32 v197, v197, v85
	v_add_f32_e32 v198, v198, v69
	v_add_f32_e32 v197, v197, v86
	v_add_f32_e32 v198, v198, v70
	v_add_f32_e32 v197, v197, v87
	v_add_f32_e32 v198, v198, v71
	v_add_f32_e32 v197, v197, v88
	v_add_f32_e32 v198, v198, v72
	v_add_f32_e32 v197, v197, v89
	v_add_f32_e32 v198, v198, v73
	v_add_f32_e32 v197, v197, v90
	v_add_f32_e32 v198, v198, v74
	v_add_f32_e32 v197, v197, v91
	v_add_f32_e32 v198, v198, v75
	v_add_f32_e32 v197, v197, v92
	v_add_f32_e32 v198, v198, v76
	v_add_f32_e32 v197, v197, v93
	v_add_f32_e32 v198, v198, v77
	v_add_f32_e32 v197, v197, v94
	v_add_f32_e32 v198, v198, v78
	v_add_f32_e32 v197, v197, v95
	v_add_f32_e32 v198, v198, v79
	v_max_f32_e32 v199, v197, v198
	v_cmp_ngt_f32_e32 vcc, 0x5d800000, v199
	s_cbranch_vccnz .Latt_redo
	v_add_f32_e32 v149, v149, v197
	v_add_f32_e32 v148, v148, v198
	v_cvt_pk_bf16_f32 v80, v80, v81
	v_cvt_pk_bf16_f32 v81, v82, v83
	v_cvt_pk_bf16_f32 v82, v84, v85
	v_cvt_pk_bf16_f32 v83, v86, v87
	v_cvt_pk_bf16_f32 v84, v88, v89
	v_cvt_pk_bf16_f32 v85, v90, v91
	v_cvt_pk_bf16_f32 v86, v92, v93
	v_cvt_pk_bf16_f32 v87, v94, v95
	v_cvt_pk_bf16_f32 v64, v64, v65
	v_cvt_pk_bf16_f32 v65, v66, v67
	v_cvt_pk_bf16_f32 v66, v68, v69
	v_cvt_pk_bf16_f32 v67, v70, v71
	v_cvt_pk_bf16_f32 v68, v72, v73
	v_cvt_pk_bf16_f32 v69, v74, v75
	v_cvt_pk_bf16_f32 v70, v76, v77
	v_cvt_pk_bf16_f32 v71, v78, v79
	s_cmpk_eq_i32 s13, 0x60
	s_cbranch_scc1 .Latt_pv
	s_mov_b32 s25, 1
	s_setprio 1
	s_waitcnt lgkmcnt(3)
	v_mfma_f32_32x32x16_bf16 v[32:47], v[164:167], v[80:83], v[32:47]
	v_mfma_f32_32x32x16_bf16 v[16:31], v[164:167], v[64:67], v[16:31]
	ds_read_b128 v[164:167], v189 offset:4640
	s_waitcnt lgkmcnt(3)
	v_mfma_f32_32x32x16_bf16 v[48:63], v[168:171], v[80:83], v[48:63]
	v_mfma_f32_32x32x16_bf16 v[0:15], v[168:171], v[64:67], v[0:15]
	ds_read_b128 v[64:67], v189 offset:4608
	ds_read_b128 v[168:171], v189 offset:4672
	s_waitcnt lgkmcnt(4)
	v_mfma_f32_32x32x16_bf16 v[32:47], v[172:175], v[84:87], v[32:47]
	v_mfma_f32_32x32x16_bf16 v[16:31], v[172:175], v[68:71], v[16:31]
	ds_read_b128 v[172:175], v189 offset:4704
	s_waitcnt lgkmcnt(4)
	v_mfma_f32_32x32x16_bf16 v[48:63], v[238:241], v[84:87], v[48:63]
	v_mfma_f32_32x32x16_bf16 v[0:15], v[238:241], v[68:71], v[0:15]
	s_setprio 0
	s_branch .Latt_tail
.Latt_redo:
	s_mov_b32 s24, 1
	s_mov_b32 s25, 0
	s_branch .Latt_noskip

.Latt_pv:
	s_mov_b32 s25, 0
	s_setprio 1
	s_waitcnt lgkmcnt(3)
	v_mfma_f32_32x32x16_bf16 v[32:47], v[164:167], v[80:83], v[32:47]
	v_mfma_f32_32x32x16_bf16 v[16:31], v[164:167], v[64:67], v[16:31]
	s_waitcnt lgkmcnt(2)
	v_mfma_f32_32x32x16_bf16 v[48:63], v[168:171], v[80:83], v[48:63]
	v_mfma_f32_32x32x16_bf16 v[0:15], v[168:171], v[64:67], v[0:15]
	s_waitcnt lgkmcnt(1)
	v_mfma_f32_32x32x16_bf16 v[32:47], v[172:175], v[84:87], v[32:47]
	v_mfma_f32_32x32x16_bf16 v[16:31], v[172:175], v[68:71], v[16:31]
	s_waitcnt lgkmcnt(0)
	v_mfma_f32_32x32x16_bf16 v[48:63], v[238:241], v[84:87], v[48:63]
	v_mfma_f32_32x32x16_bf16 v[0:15], v[238:241], v[68:71], v[0:15]
	s_setprio 0
	s_branch .Latt_tail
.Latt_skipkt:
	s_mov_b32 s25, 0
